# in-proj A tile order WGM 8->4 (per XCD round 4 pm x 8 pn) on top of v54
# speedup vs baseline: 1.0065x; 1.0003x over previous
;     __host__ __device__ bool next(int i, Unit& u) const {
;         const long L = (long)i * G + c; if (L >= nwg) return false;
;         int wgid = (int)L; { const int q = nwg / NXCD, r = nwg % NXCD, xcd = wgid % NXCD, off = wgid / NXCD; wgid = (xcd < r ? xcd * (q + 1) : r * (q + 1) + (xcd - r) * q) + off; }
;         const int nig = WGM * nN, gid = wgid / nig, fm = gid * WGM, gsz = (nM - fm) < WGM ? (nM - fm) : WGM;
;         u.pm = fm + ((wgid % nig) % gsz); u.pn = (wgid % nig) / gsz; return true;
.LBB0_185:
	s_add_u32 s63, s42, 0x2400000
	s_addc_u32 s64, s43, 0
	s_add_u32 s46, s42, 0x6400000
	s_addc_u32 s47, s43, 0
	s_add_u32 s50, s42, 0xf400000
	s_addc_u32 s51, s43, 0
	v_writelane_b32 v253, s30, 55
	s_cmpk_lt_i32 s87, 0x500
	s_cselect_b64 s[0:1], -1, 0
	v_writelane_b32 v253, s31, 56
	v_writelane_b32 v253, s0, 57
	s_ashr_i32 s7, s3, 31
	s_add_i32 s2, s3, 0xff
	v_writelane_b32 v253, s1, 58
	s_ashr_i32 s0, s87, 31
	v_writelane_b32 v253, s0, 59
	s_lshr_b32 s0, s0, 29
	s_add_i32 s0, s87, s0
	s_ashr_i32 s4, s0, 3
	s_and_b32 s0, s0, -8
	s_sub_i32 s5, s87, s0
	s_add_u32 s91, s42, 0xc400000
	s_addc_u32 s33, s43, 0
	s_add_u32 s0, s42, 0x8000
	v_writelane_b32 v253, s0, 60
	v_writelane_b32 v253, s40, 61
	s_addc_u32 s0, s43, 0
	s_cmp_lt_i32 s5, 0
	v_writelane_b32 v252, s43, 0
	v_writelane_b32 v252, s0, 1
	s_cselect_b64 s[0:1], -1, 0
	v_writelane_b32 v252, s0, 2
	s_movk_i32 s6, 0xa1
	v_writelane_b32 v253, s41, 62
	v_writelane_b32 v252, s1, 3
	s_and_b64 s[0:1], s[0:1], exec
	s_cselect_b32 s0, s6, 0xa0
	s_mul_i32 s0, s5, s0
	s_add_i32 s0, s0, s4
	v_writelane_b32 v252, s5, 4
	s_mul_hi_i32 s1, s0, 0x66666667
	v_writelane_b32 v252, s4, 5
	s_lshr_b32 s4, s1, 31
	s_ashr_i32 s1, s1, 6
	s_add_i32 s1, s1, s4
	s_lshl_b32 s4, s1, 2
	s_mulk_i32 s1, 0xa0
	s_sub_i32 s1, s0, s1
	s_bfe_u32 s0, s1, 0x2001c
	s_add_i32 s5, s1, s0
	s_sext_i32_i16 s6, s5
	s_and_b32 s5, s5, 0xfffc
	s_sub_i32 s1, s1, s5
	s_sext_i32_i16 s1, s1
	s_add_i32 s8, s4, s1
	s_ashr_i32 s1, s6, 2
	v_writelane_b32 v252, s1, 6
	s_mov_b32 s4, s8
	s_ashr_i32 s9, s8, 31
	v_writelane_b32 v252, s4, 7
	s_lshr_b32 s0, s6, 2
	v_writelane_b32 v253, s42, 63
	v_writelane_b32 v252, s5, 8
	s_lshl_b64 s[4:5], s[8:9], 19
	v_writelane_b32 v252, s4, 9
	s_bfe_i64 s[0:1], s[0:1], 0x100000
	s_lshl_b64 s[0:1], s[0:1], 19
	v_writelane_b32 v252, s5, 10
	v_readlane_b32 s4, v253, 18
	v_readlane_b32 s5, v253, 19
	s_add_u32 s0, s4, s0
	s_addc_u32 s1, s5, s1
	s_add_u32 s4, s0, 0x10000
	s_addc_u32 s5, s1, 0
	v_writelane_b32 v252, s4, 11
	s_movk_i32 s93, 0xc0
	v_mov_b32_e32 v161, 0
	v_writelane_b32 v252, s5, 12
	s_add_u32 s4, s0, 0x10080
	v_writelane_b32 v252, s0, 13
	s_addc_u32 s5, s1, 0
	s_abs_i32 s6, s3
	v_cvt_f32_u32_e32 v0, s6
	v_writelane_b32 v252, s1, 14
	s_sub_i32 s0, 0, s6
	v_writelane_b32 v252, s4, 15
	v_rcp_iflag_f32_e32 v0, v0
	v_mov_b32_e32 v190, 0x358637bd
	v_writelane_b32 v252, s5, 16
	v_writelane_b32 v252, s7, 17
	v_mul_f32_e32 v0, 0x4f7ffffe, v0
	v_cvt_u32_f32_e32 v0, v0
	v_mov_b32_e32 v191, 1
	s_mov_b64 s[10:11], 0x840
	s_mov_b32 s96, 0x2aaaaaab
	v_readfirstlane_b32 s1, v0
	s_mul_i32 s0, s0, s1
	s_mul_hi_u32 s0, s1, s0
	s_add_i32 s8, s1, s0
	s_mul_hi_u32 s0, s8, 0x500
	s_mul_i32 s1, s0, s6
	s_sub_i32 s1, 0x500, s1
	s_add_i32 s4, s0, 1
	s_sub_i32 s5, s1, s6
	s_cmp_ge_u32 s1, s6
	s_cselect_b32 s0, s4, s0
	s_cselect_b32 s1, s5, s1
	s_add_i32 s4, s0, 1
	s_cmp_ge_u32 s1, s6
	s_cselect_b32 s0, s4, s0
	s_xor_b32 s0, s0, s7
	s_abs_i32 s1, s2
	s_sub_i32 s43, s0, s7
	s_ashr_i32 s0, s2, 31
	s_mul_hi_u32 s2, s1, s8
	s_mul_i32 s4, s2, s6
	s_sub_i32 s1, s1, s4
	s_xor_b32 s0, s0, s7
	s_add_i32 s4, s2, 1
	s_sub_i32 s5, s1, s6
	s_cmp_ge_u32 s1, s6
	s_cselect_b32 s2, s4, s2
	s_cselect_b32 s1, s5, s1
	s_add_i32 s4, s2, 1
	s_cmp_ge_u32 s1, s6
	s_cselect_b32 s1, s4, s2
	s_xor_b32 s1, s1, s0
	s_sub_i32 s0, s1, s0
	s_mul_i32 s58, s0, s60
	s_sub_i32 s1, 0x100, s58
	v_writelane_b32 v252, s8, 18
	s_min_i32 s59, s0, s1
	v_writelane_b32 v252, s6, 19
	s_cmp_gt_i32 s59, 0
	v_writelane_b32 v252, s60, 20
	s_cselect_b64 s[0:1], -1, 0
	v_writelane_b32 v252, s0, 21
	s_mul_i32 s43, s43, s87
	s_mov_b64 s[6:7], 0x800
	v_writelane_b32 v252, s1, 22
	s_lshl_b32 s1, s58, 5
	s_and_b32 s4, s1, 0xe0
	s_and_b32 s1, s58, 7
	s_sub_i32 s1, 2, s1
	s_max_i32 s2, s1, 0
	s_xor_b32 s1, s4, 0xe0
	s_lshr_b32 s1, s1, 5
	v_writelane_b32 v252, s4, 23
	s_min_u32 s4, s1, 2
	s_ashr_i32 s1, s58, 3
	s_bfe_u32 s0, s58, 0x40003
	s_and_b32 s1, s1, -16
	s_or_b32 s0, s1, s0
	s_ashr_i32 s1, s0, 31
	s_lshl_b64 s[0:1], s[0:1], 19
	s_add_u32 s0, s91, s0
	s_addc_u32 s1, s33, s1
	s_lshl_b32 s5, s2, 5
	v_writelane_b32 v252, s5, 24
	s_sub_i32 s5, s5, 64
	v_writelane_b32 v252, s5, 25
	s_add_u32 s5, s0, 0x1000000
	v_writelane_b32 v252, s5, 26
	s_addc_u32 s5, s1, 0
	v_writelane_b32 v252, s5, 27
	s_add_u32 s5, s0, 0x2000000
	v_writelane_b32 v252, s5, 28
	v_writelane_b32 v252, s0, 29
	s_mov_b64 s[8:9], 0x880
	s_movk_i32 s97, 0xff40
	v_writelane_b32 v252, s1, 30
	s_addc_u32 s0, s1, 0
	v_writelane_b32 v252, s0, 31
	s_sub_i32 s0, s4, s2
	s_add_i32 s0, s0, 3
	v_writelane_b32 v252, s0, 32
	s_sub_i32 s0, 4, s2
	v_writelane_b32 v252, s0, 33
	s_lshl_b32 s0, s58, 2
	s_and_b32 s92, s0, 0x1e0
	s_add_i32 s0, 0, 0x26160
	v_writelane_b32 v252, s0, 34
	s_add_i32 s0, 0, 0x26164
	v_writelane_b32 v252, s0, 35
	v_writelane_b32 v252, s65, 36
	v_writelane_b32 v252, s66, 37
	s_mov_b64 s[4:5], 0x80
	s_movk_i32 s0, 0x5f
	v_writelane_b32 v252, s67, 38
	v_writelane_b32 v252, s63, 39
	v_writelane_b32 v252, s64, 40
	s_add_i32 s1, 0, 0x11800
	s_movk_i32 s98, 0x41
	s_movk_i32 s99, 0x5a
	s_movk_i32 s68, 0xa6
	s_movk_i32 s69, 0x130
	s_movk_i32 s70, 0x22e
	s_mov_b32 s71, 0x3fb8aa3b
	s_movk_i32 s84, 0x88
	s_add_i32 s90, 0, 0x11000
	v_mov_b32_e32 v192, 0x300
	v_mov_b32_e32 v193, 0x200
	v_mov_b64_e32 v[162:163], 0x500
	v_mov_b64_e32 v[164:165], 0x4ff
	s_mov_b32 s85, 0
	v_writelane_b32 v252, s87, 41
	v_writelane_b32 v252, s92, 42
	s_branch .LBB0_190

;     __host__ __device__ bool next(int i, Unit& u) const {
;         const long L = (long)i * G + c; if (L >= nwg) return false;
;         int wgid = (int)L; { const int q = nwg / NXCD, r = nwg % NXCD, xcd = wgid % NXCD, off = wgid / NXCD; wgid = (xcd < r ? xcd * (q + 1) : r * (q + 1) + (xcd - r) * q) + off; }
;         const int nig = WGM * nN, gid = wgid / nig, fm = gid * WGM, gsz = (nM - fm) < WGM ? (nM - fm) : WGM;
;         u.pm = fm + ((wgid % nig) % gsz); u.pn = (wgid % nig) / gsz; return true;
.LBB0_203:
	s_add_i32 s42, s27, 1
	v_readlane_b32 s2, v252, 17
	s_mul_i32 s2, s42, s2
	s_mul_hi_u32 s29, s42, s3
	s_add_i32 s29, s29, s2
	s_mul_i32 s2, s42, s3
	s_add_u32 s48, s2, s87
	v_readlane_b32 s2, v253, 59
	s_addc_u32 s49, s29, s2
	v_cmp_gt_i64_e32 vcc, s[48:49], v[164:165]
	v_cmp_lt_i64_e64 s[36:37], s[48:49], v[162:163]
	s_cbranch_vccnz .LBB0_205
	s_ashr_i32 s2, s48, 31
	s_lshr_b32 s2, s2, 29
	s_add_i32 s2, s48, s2
	s_ashr_i32 s28, s2, 3
	s_and_b32 s2, s2, -8
	s_sub_i32 s2, s48, s2
	s_cmp_lt_i32 s2, 0
	s_movk_i32 s29, 0xa1
	s_cselect_b32 s29, s29, 0xa0
	s_mul_i32 s2, s2, s29
	s_add_i32 s2, s2, s28
	s_mul_hi_i32 s28, s2, 0x66666667
	s_lshr_b32 s29, s28, 31
	s_ashr_i32 s28, s28, 6
	s_add_i32 s28, s28, s29
	s_lshl_b32 s29, s28, 2
	s_sub_i32 s30, 32, s29
	s_min_i32 s30, s30, 4
	s_abs_i32 s31, s30
	s_waitcnt lgkmcnt(0)
	v_cvt_f32_u32_e32 v144, s31
	s_sub_i32 s49, 0, s31
	s_mulk_i32 s28, 0xa0
	s_sub_i32 s2, s2, s28
	v_rcp_iflag_f32_e32 v144, v144
	s_abs_i32 s28, s2
	s_xor_b32 s48, s2, s30
	s_ashr_i32 s48, s48, 31
	v_mul_f32_e32 v144, 0x4f7ffffe, v144
	v_cvt_u32_f32_e32 v144, v144
	s_nop 0
	v_readfirstlane_b32 s60, v144
	s_mul_i32 s49, s49, s60
	s_mul_hi_u32 s49, s60, s49
	s_add_i32 s60, s60, s49
	s_mul_hi_u32 s49, s28, s60
	s_mul_i32 s60, s49, s31
	s_sub_i32 s28, s28, s60
	s_add_i32 s61, s49, 1
	s_sub_i32 s60, s28, s31
	s_cmp_ge_u32 s28, s31
	s_cselect_b32 s49, s61, s49
	s_cselect_b32 s28, s60, s28
	s_add_i32 s60, s49, 1
	s_cmp_ge_u32 s28, s31
	s_cselect_b32 s28, s60, s49
	s_xor_b32 s28, s28, s48
	s_sub_i32 s28, s28, s48
	s_mul_i32 s30, s28, s30
	s_sub_i32 s2, s2, s30
	s_add_i32 s30, s29, s2
